# FoX attention loop: redundant bias copies removed (MFMA reads bias as C directly), 32 subtracts packed into 16 v_pk_add
# speedup vs baseline: 1.0119x; 1.0009x over previous
; template <bool FOX> ...
;     ...
;   for (int kt = kt0; kt < kt1; ++kt) {
;     const int k0 = kt * 32;
;     bf16x8 av[2][2];
; #pragma unroll
;     for (int dt = 0; dt < 2; ++dt)
; #pragma unroll
;       for (int ks = 0; ks < 2; ++ks) av[dt][ks] = *reinterpret_cast<const bf16x8*>(vp + (dt * 2 + ks) * 512);
;     f32x16 st[2];
; #pragma unroll
;     for (int qt = 0; qt < 2; ++qt) {
;       st[qt] = mfma32(ak[0], bq[qt][0], negc);
; #pragma unroll
;       for (int kk = 1; kk < 4; ++kk) st[qt] = mfma32(ak[kk], bq[qt][kk], st[qt]);
;     }
;     kp += 2048;
;     vp += 2048;
;     cp += 32;
;     if (kt + 1 < kt1) {
; #pragma unroll
;       for (int kk = 0; kk < 4; ++kk) ak[kk] = *reinterpret_cast<const bf16x8*>(kp + kk * 512);
;       if (FOX) {
; #pragma unroll
;         for (int jj = 0; jj < 4; ++jj) {
;           f32x4 cv = *reinterpret_cast<const f32x4*>(cp + 8 * jj);
;           negc[4 * jj + 0] = cv[0]; negc[4 * jj + 1] = cv[1]; negc[4 * jj + 2] = cv[2]; negc[4 * jj + 3] = cv[3];
;         }
;       }
.LBB0_508:
	v_lshl_add_u64 v[194:195], s[90:91], 0, v[190:191]
	s_mov_b32 s11, 0x1d840000
	v_add_co_u32_e32 v80, vcc, s11, v194
	s_waitcnt vmcnt(0)
	v_mfma_f32_32x32x16_bf16 v[96:111], v[158:161], v[114:117], v[64:79]
	v_addc_co_u32_e32 v81, vcc, 0, v195, vcc
	global_load_dwordx4 v[174:177], v[80:81], off
	global_load_dwordx4 v[170:173], v[80:81], off offset:1024
	global_load_dwordx4 v[166:169], v[80:81], off offset:2048
	global_load_dwordx4 v[162:165], v[80:81], off offset:3072
	v_mfma_f32_32x32x16_bf16 v[96:111], v[154:157], v[118:121], v[96:111]
	s_add_i32 s9, s9, 1
	s_cmp_ge_i32 s9, s8
	v_mfma_f32_32x32x16_bf16 v[80:95], v[158:161], v[130:133], v[64:79]
	v_mfma_f32_32x32x16_bf16 v[80:95], v[154:157], v[134:137], v[80:95]
	v_mfma_f32_32x32x16_bf16 v[96:111], v[150:153], v[122:125], v[96:111]
	v_mfma_f32_32x32x16_bf16 v[80:95], v[150:153], v[138:141], v[80:95]
	v_mfma_f32_32x32x16_bf16 v[96:111], v[146:149], v[126:129], v[96:111]
	v_mfma_f32_32x32x16_bf16 v[80:95], v[146:149], v[142:145], v[80:95]
	s_cbranch_scc1 .LBB0_510
	s_nop 1
	v_add_co_u32_e32 v66, vcc, 0x1f841000, v194
	v_lshl_add_u64 v[64:65], s[90:91], 0, v[192:193]
	s_nop 0
	v_addc_co_u32_e32 v67, vcc, 0, v195, vcc
	v_add_co_u32_e32 v76, vcc, 0x22be0000, v64
	global_load_dwordx4 v[158:161], v[66:67], off
	global_load_dwordx4 v[154:157], v[66:67], off offset:1024
	global_load_dwordx4 v[150:153], v[66:67], off offset:2048
	global_load_dwordx4 v[146:149], v[66:67], off offset:3072
	v_addc_co_u32_e32 v77, vcc, 0, v65, vcc
	global_load_dwordx4 v[64:67], v[76:77], off offset:128
	global_load_dwordx4 v[68:71], v[76:77], off offset:160
	global_load_dwordx4 v[72:75], v[76:77], off offset:192
	s_nop 0
	global_load_dwordx4 v[76:79], v[76:77], off offset:224

; __device__ __forceinline__ float ex2(float x) { return __builtin_amdgcn_exp2f(x); }
; template <bool FOX> ...
;     ...
; #pragma unroll
;     for (int qt = 0; qt < 2; ++qt) {
;       float mx = fmaxf(fmaxf(st[qt][0], st[qt][1]), fmaxf(st[qt][2], st[qt][3]));
; #pragma unroll
;       for (int r = 4; r < 16; r += 4) mx = fmaxf(fmaxf(mx, st[qt][r]), fmaxf(fmaxf(st[qt][r + 1], st[qt][r + 2]), st[qt][r + 3]));
;       mx = xmax32(mx);
;       const float mnew = fmaxf(mrun[qt], mx);
;       const float alpha = ex2(mrun[qt] - mnew);
;       mrun[qt] = mnew;
;       float ps0 = 0.f, ps1 = 0.f;
; #pragma unroll
;       for (int r = 0; r < 16; r += 2) {
;         float p0 = ex2(st[qt][r] - mnew), p1 = ex2(st[qt][r + 1] - mnew);
;         ps0 += p0; ps1 += p1;
;         st[qt][r] = p0; st[qt][r + 1] = p1;
;       }
;       lrun[qt] = lrun[qt] * alpha + (ps0 + ps1);
; #pragma unroll
;       for (int dt = 0; dt < 2; ++dt) o[dt][qt] = o[dt][qt] * alpha;
; #pragma unroll
;       for (int ks = 0; ks < 2; ++ks) {
;         union { bf16x8 v; uint32_t w[4]; } u;
; #pragma unroll
;         for (int e = 0; e < 4; ++e) u.w[e] = pack2(st[qt][8 * ks + 2 * e], st[qt][8 * ks + 2 * e + 1]);
;         bp[qt][ks] = u.v;
;       }
;     }
.LBB0_512:
	s_nop 7
	v_max_f32_e32 v182, v99, v99
	v_max_f32_e32 v194, v98, v98
	v_max_f32_e32 v182, v194, v182
	v_max3_f32 v182, v96, v97, v182
	v_max3_f32 v194, v101, v102, v103
	v_max3_f32 v182, v182, v100, v194
	v_max3_f32 v194, v105, v106, v107
	v_max3_f32 v182, v182, v104, v194
	v_max3_f32 v194, v109, v110, v111
	v_max3_f32 v182, v182, v108, v194
	v_mov_b32_e32 v194, v182
	s_nop 1
	v_permlane32_swap_b32_e32 v182, v194
	v_max3_f32 v182, v185, v182, v194
	v_pk_add_f32 v[96:97], v[96:97], v[182:183] op_sel_hi:[1,0] neg_lo:[0,1] neg_hi:[0,1]
	v_pk_add_f32 v[98:99], v[98:99], v[182:183] op_sel_hi:[1,0] neg_lo:[0,1] neg_hi:[0,1]
	v_pk_add_f32 v[100:101], v[100:101], v[182:183] op_sel_hi:[1,0] neg_lo:[0,1] neg_hi:[0,1]
	v_pk_add_f32 v[102:103], v[102:103], v[182:183] op_sel_hi:[1,0] neg_lo:[0,1] neg_hi:[0,1]
	v_exp_f32_e32 v194, v96
	v_exp_f32_e32 v196, v97
	v_exp_f32_e32 v198, v98
	v_exp_f32_e32 v200, v99
	v_exp_f32_e32 v202, v100
	v_exp_f32_e32 v204, v101
	v_exp_f32_e32 v206, v102
	v_exp_f32_e32 v208, v103
	v_pk_add_f32 v[96:97], v[104:105], v[182:183] op_sel_hi:[1,0] neg_lo:[0,1] neg_hi:[0,1]
	v_pk_add_f32 v[106:107], v[106:107], v[182:183] op_sel_hi:[1,0] neg_lo:[0,1] neg_hi:[0,1]
	v_pk_add_f32 v[108:109], v[108:109], v[182:183] op_sel_hi:[1,0] neg_lo:[0,1] neg_hi:[0,1]
	v_pk_add_f32 v[110:111], v[110:111], v[182:183] op_sel_hi:[1,0] neg_lo:[0,1] neg_hi:[0,1]
	v_max_f32_e32 v104, v83, v83
	v_max_f32_e32 v105, v82, v82
	v_max_f32_e32 v104, v105, v104
	v_max3_f32 v104, v80, v81, v104
	v_max3_f32 v105, v85, v86, v87
	v_max3_f32 v104, v104, v84, v105
	v_max3_f32 v105, v89, v90, v91
	v_max3_f32 v104, v104, v88, v105
	v_max3_f32 v105, v93, v94, v95
	v_max3_f32 v104, v104, v92, v105
	v_mov_b32_e32 v105, v104
	s_nop 1
	v_permlane32_swap_b32_e32 v104, v105
	v_max3_f32 v104, v113, v104, v105
	v_exp_f32_e32 v210, v96
	v_exp_f32_e32 v212, v97
	v_exp_f32_e32 v106, v106
	v_exp_f32_e32 v214, v107
	v_exp_f32_e32 v108, v108
	v_exp_f32_e32 v216, v109
	v_exp_f32_e32 v110, v110
	v_exp_f32_e32 v234, v111
	v_pk_add_f32 v[80:81], v[80:81], v[104:105] op_sel_hi:[1,0] neg_lo:[0,1] neg_hi:[0,1]
	v_pk_add_f32 v[82:83], v[82:83], v[104:105] op_sel_hi:[1,0] neg_lo:[0,1] neg_hi:[0,1]
	v_pk_add_f32 v[84:85], v[84:85], v[104:105] op_sel_hi:[1,0] neg_lo:[0,1] neg_hi:[0,1]
	v_pk_add_f32 v[86:87], v[86:87], v[104:105] op_sel_hi:[1,0] neg_lo:[0,1] neg_hi:[0,1]
	v_pk_add_f32 v[88:89], v[88:89], v[104:105] op_sel_hi:[1,0] neg_lo:[0,1] neg_hi:[0,1]
	v_pk_add_f32 v[90:91], v[90:91], v[104:105] op_sel_hi:[1,0] neg_lo:[0,1] neg_hi:[0,1]
	v_pk_add_f32 v[92:93], v[92:93], v[104:105] op_sel_hi:[1,0] neg_lo:[0,1] neg_hi:[0,1]
	v_pk_add_f32 v[94:95], v[94:95], v[104:105] op_sel_hi:[1,0] neg_lo:[0,1] neg_hi:[0,1]
	v_exp_f32_e32 v195, v80
	v_exp_f32_e32 v197, v81
	v_exp_f32_e32 v199, v82
	v_exp_f32_e32 v201, v83
	v_exp_f32_e32 v203, v84
	v_exp_f32_e32 v205, v85
	v_exp_f32_e32 v207, v86
	v_exp_f32_e32 v209, v87
	v_exp_f32_e32 v211, v88
	v_exp_f32_e32 v213, v89
	v_exp_f32_e32 v107, v90
	v_exp_f32_e32 v215, v91
	v_exp_f32_e32 v109, v92
	v_exp_f32_e32 v217, v93
	v_exp_f32_e32 v111, v94
	v_exp_f32_e32 v235, v95
	v_sub_f32_e32 v185, v185, v182
	v_pk_add_f32 v[80:81], v[194:195], 0 op_sel_hi:[1,0]
	v_pk_add_f32 v[82:83], v[196:197], 0 op_sel_hi:[1,0]
	v_exp_f32_e32 v236, v185
	v_pk_add_f32 v[80:81], v[198:199], v[80:81]
	v_pk_add_f32 v[82:83], v[200:201], v[82:83]
	v_pk_add_f32 v[80:81], v[202:203], v[80:81]
	v_pk_add_f32 v[82:83], v[204:205], v[82:83]
	v_pk_add_f32 v[80:81], v[206:207], v[80:81]
	v_pk_add_f32 v[82:83], v[208:209], v[82:83]
	v_sub_f32_e32 v105, v113, v104
	v_pk_add_f32 v[80:81], v[210:211], v[80:81]
	v_pk_add_f32 v[82:83], v[212:213], v[82:83]
	v_pk_mul_f32 v[62:63], v[62:63], v[236:237] op_sel_hi:[1,0]
	v_pk_mul_f32 v[60:61], v[60:61], v[236:237] op_sel_hi:[1,0]
	v_pk_mul_f32 v[58:59], v[58:59], v[236:237] op_sel_hi:[1,0]
	v_pk_mul_f32 v[56:57], v[56:57], v[236:237] op_sel_hi:[1,0]
	v_pk_mul_f32 v[54:55], v[54:55], v[236:237] op_sel_hi:[1,0]
	v_pk_mul_f32 v[52:53], v[52:53], v[236:237] op_sel_hi:[1,0]
	v_pk_mul_f32 v[50:51], v[50:51], v[236:237] op_sel_hi:[1,0]
	v_pk_mul_f32 v[48:49], v[48:49], v[236:237] op_sel_hi:[1,0]
	v_pk_mul_f32 v[46:47], v[46:47], v[236:237] op_sel_hi:[1,0]
	v_pk_mul_f32 v[44:45], v[44:45], v[236:237] op_sel_hi:[1,0]
	v_pk_mul_f32 v[42:43], v[42:43], v[236:237] op_sel_hi:[1,0]
	v_pk_mul_f32 v[40:41], v[40:41], v[236:237] op_sel_hi:[1,0]
	v_pk_mul_f32 v[38:39], v[38:39], v[236:237] op_sel_hi:[1,0]
	v_pk_mul_f32 v[36:37], v[36:37], v[236:237] op_sel_hi:[1,0]
	v_pk_mul_f32 v[34:35], v[34:35], v[236:237] op_sel_hi:[1,0]
	v_pk_mul_f32 v[32:33], v[32:33], v[236:237] op_sel_hi:[1,0]
	v_exp_f32_e32 v237, v105
	v_pk_add_f32 v[80:81], v[106:107], v[80:81]
	v_pk_add_f32 v[82:83], v[214:215], v[82:83]
	v_pk_add_f32 v[80:81], v[108:109], v[80:81]
	v_pk_add_f32 v[82:83], v[216:217], v[82:83]
	v_pk_add_f32 v[80:81], v[110:111], v[80:81]
	v_pk_add_f32 v[82:83], v[234:235], v[82:83]
	v_cvt_pk_bf16_f32 v100, v194, v196
	v_cvt_pk_bf16_f32 v101, v198, v200
	v_cvt_pk_bf16_f32 v102, v202, v204
	v_cvt_pk_bf16_f32 v103, v206, v208
	v_cvt_pk_bf16_f32 v84, v195, v197
	s_nop 0
	v_pk_add_f32 v[80:81], v[80:81], v[82:83]
	v_cvt_pk_bf16_f32 v85, v199, v201
	v_cvt_pk_bf16_f32 v86, v203, v205
	v_cvt_pk_bf16_f32 v87, v207, v209
	s_waitcnt vmcnt(3)
; template <bool FOX> ...
;     ...
;       lrun[qt] = lrun[qt] * alpha + (ps0 + ps1);
; #pragma unroll
;       for (int dt = 0; dt < 2; ++dt) o[dt][qt] = o[dt][qt] * alpha;
; #pragma unroll
;       for (int ks = 0; ks < 2; ++ks) {
;         union { bf16x8 v; uint32_t w[4]; } u;
; #pragma unroll
;         for (int e = 0; e < 4; ++e) u.w[e] = pack2(st[qt][8 * ks + 2 * e], st[qt][8 * ks + 2 * e + 1]);
;         bp[qt][ks] = u.v;
;       }
;     }
; #pragma unroll
;     for (int dt = 0; dt < 2; ++dt)
; #pragma unroll
;       for (int qt = 0; qt < 2; ++qt)
; #pragma unroll
;         for (int ks = 0; ks < 2; ++ks) o[dt][qt] = mfma32(av[dt][ks], bp[qt][ks], o[dt][qt]);
	v_mfma_f32_32x32x16_bf16 v[48:63], v[174:177], v[100:103], v[48:63]
	v_fma_f32 v188, v188, v236, v80
	v_fma_f32 v189, v189, v237, v81
	v_mov_b32_e32 v80, v237
	v_mul_f32_e64 v30, v30, v80
	v_mul_f32_e64 v31, v31, v80
	v_pk_mul_f32 v[28:29], v[28:29], v[80:81] op_sel_hi:[1,0]
	v_pk_mul_f32 v[26:27], v[26:27], v[80:81] op_sel_hi:[1,0]
	v_pk_mul_f32 v[24:25], v[24:25], v[80:81] op_sel_hi:[1,0]
	v_pk_mul_f32 v[22:23], v[22:23], v[80:81] op_sel_hi:[1,0]
	v_pk_mul_f32 v[20:21], v[20:21], v[80:81] op_sel_hi:[1,0]
	v_pk_mul_f32 v[18:19], v[18:19], v[80:81] op_sel_hi:[1,0]
	v_pk_mul_f32 v[16:17], v[16:17], v[80:81] op_sel_hi:[1,0]
	v_pk_mul_f32 v[14:15], v[14:15], v[80:81] op_sel_hi:[1,0]
	v_pk_mul_f32 v[12:13], v[12:13], v[80:81] op_sel_hi:[1,0]
	v_pk_mul_f32 v[10:11], v[10:11], v[80:81] op_sel_hi:[1,0]
	v_pk_mul_f32 v[8:9], v[8:9], v[80:81] op_sel_hi:[1,0]
	v_pk_mul_f32 v[6:7], v[6:7], v[80:81] op_sel_hi:[1,0]
	v_pk_mul_f32 v[4:5], v[4:5], v[80:81] op_sel_hi:[1,0]
	v_pk_mul_f32 v[2:3], v[2:3], v[80:81] op_sel_hi:[1,0]
	v_pk_mul_f32 v[0:1], v[0:1], v[80:81] op_sel_hi:[1,0]
	v_mfma_f32_32x32x16_bf16 v[16:31], v[174:177], v[84:87], v[16:31]
	v_cvt_pk_bf16_f32 v96, v210, v212
	v_cvt_pk_bf16_f32 v97, v106, v214
	v_cvt_pk_bf16_f32 v98, v108, v216
	v_cvt_pk_bf16_f32 v99, v110, v234
	v_cvt_pk_bf16_f32 v80, v211, v213
	v_cvt_pk_bf16_f32 v81, v107, v215
	v_cvt_pk_bf16_f32 v82, v109, v217
	s_waitcnt vmcnt(1)
	v_mfma_f32_32x32x16_bf16 v[32:47], v[166:169], v[100:103], v[32:47]
	v_cvt_pk_bf16_f32 v83, v111, v235
	s_add_i32 s10, s10, 32
	v_lshl_add_u64 v[190:191], v[190:191], 0, s[68:69]
	v_lshl_add_u64 v[192:193], v[192:193], 0, s[86:87]
	s_cmp_eq_u32 s8, s9
	v_mfma_f32_32x32x16_bf16 v[0:15], v[166:169], v[84:87], v[0:15]
	v_mfma_f32_32x32x16_bf16 v[48:63], v[170:173], v[96:99], v[48:63]
	v_mfma_f32_32x32x16_bf16 v[16:31], v[170:173], v[80:83], v[16:31]
	s_waitcnt vmcnt(0)
	v_mfma_f32_32x32x16_bf16 v[32:47], v[162:165], v[96:99], v[32:47]
	v_mfma_f32_32x32x16_bf16 v[0:15], v[162:165], v[80:83], v[0:15]
	s_cbranch_scc1 .LBB0_505
	v_mov_b32_e32 v185, v182
	v_mov_b32_e32 v113, v104
	s_branch .LBB0_508
